# adds: w_out epilogue residual loads ring-pipelined; grid barrier after down GEMM skipped on even chunks (next phase independent)
# speedup vs baseline: 1.2027x; 1.0028x over previous
.LBB0_1039:
	v_lshl_add_u32 v142, s75, 8, v144
	v_lshl_or_b32 v140, s74, 8, v148
	v_ashrrev_i32_e32 v143, 31, v142
	v_ashrrev_i32_e32 v141, 31, v140
	v_lshlrev_b64 v[150:151], 11, v[142:143]
	v_lshl_add_u64 v[168:169], v[150:151], 0, v[140:141]
	v_lshlrev_b64 v[170:171], 2, v[168:169]
	v_lshl_add_u64 v[172:173], s[42:43], 0, v[170:171]
	v_mov_b32_e32 v248, v172
	v_mov_b32_e32 v249, v173
	global_load_dwordx4 v[200:203], v[248:249], off
	global_load_dwordx4 v[204:207], v[248:249], off offset:16
	global_load_dwordx4 v[208:211], v[248:249], off offset:512
	global_load_dwordx4 v[212:215], v[248:249], off offset:528
	s_mov_b32 s98, 0x20000
	s_mov_b32 s99, 0
	v_lshl_add_u64 v[248:249], v[248:249], 0, s[98:99]
	global_load_dwordx4 v[216:219], v[248:249], off
	global_load_dwordx4 v[220:223], v[248:249], off offset:16
	global_load_dwordx4 v[224:227], v[248:249], off offset:512
	global_load_dwordx4 v[228:231], v[248:249], off offset:528
	s_mov_b32 s98, 0x20000
	s_mov_b32 s99, 0
	v_lshl_add_u64 v[248:249], v[248:249], 0, s[98:99]
	global_load_dwordx4 v[232:235], v[248:249], off
	global_load_dwordx4 v[236:239], v[248:249], off offset:16
	global_load_dwordx4 v[240:243], v[248:249], off offset:512
	global_load_dwordx4 v[244:247], v[248:249], off offset:528
	v_lshl_add_u64 v[168:169], v[168:169], 1, s[14:15]
	v_lshl_add_u64 v[170:171], s[54:55], 0, v[170:171]
	s_waitcnt vmcnt(10)
	v_mov_b32_e32 v150, v200
	v_mov_b32_e32 v151, v201
	v_mov_b32_e32 v152, v202
	v_mov_b32_e32 v153, v203
	v_mov_b32_e32 v154, v204
	v_mov_b32_e32 v155, v205
	v_mov_b32_e32 v156, v206
	v_mov_b32_e32 v157, v207
	s_mov_b32 s98, 0x20000
	s_mov_b32 s99, 0
	v_lshl_add_u64 v[248:249], v[248:249], 0, s[98:99]
	global_load_dwordx4 v[200:203], v[248:249], off
	global_load_dwordx4 v[204:207], v[248:249], off offset:16
	v_pk_add_f32 v[128:129], v[128:129], v[152:153]
	v_pk_add_f32 v[126:127], v[126:127], v[150:151]
	v_pk_add_f32 v[124:125], v[124:125], v[156:157]
	v_pk_add_f32 v[122:123], v[122:123], v[154:155]
	global_store_dwordx4 v[170:171], v[126:129], off
	global_store_dwordx4 v[170:171], v[122:125], off offset:16
	v_cvt_pk_bf16_f32 v150, v126, v127
	v_cvt_pk_bf16_f32 v151, v128, v129
	v_cvt_pk_bf16_f32 v152, v122, v123
	v_cvt_pk_bf16_f32 v153, v124, v125
	global_store_dwordx4 v[168:169], v[150:153], off
	s_nop 0
	v_mul_f32_e32 v127, v127, v127
	v_mul_f32_e32 v129, v129, v129
	v_mul_f32_e32 v123, v123, v123
	v_fmac_f32_e32 v127, v126, v126
	v_fmac_f32_e32 v129, v128, v128
	v_mul_f32_e32 v125, v125, v125
	v_fmac_f32_e32 v123, v122, v122
	v_add_f32_e32 v122, v127, v129
	v_fmac_f32_e32 v125, v124, v124
	v_add_f32_e32 v122, v122, v123
	v_add_f32_e32 v126, v125, v122
	s_waitcnt vmcnt(13)
	v_mov_b32_e32 v150, v208
	v_mov_b32_e32 v151, v209
	v_mov_b32_e32 v152, v210
	v_mov_b32_e32 v153, v211
	v_mov_b32_e32 v154, v212
	v_mov_b32_e32 v155, v213
	v_mov_b32_e32 v156, v214
	v_mov_b32_e32 v157, v215
	global_load_dwordx4 v[208:211], v[248:249], off offset:512
	global_load_dwordx4 v[212:215], v[248:249], off offset:528
	v_pk_add_f32 v[120:121], v[120:121], v[152:153]
	v_pk_add_f32 v[118:119], v[118:119], v[150:151]
	v_pk_add_f32 v[122:123], v[114:115], v[154:155]
	v_mul_f32_e32 v114, v119, v119
	v_mul_f32_e32 v115, v121, v121
	v_pk_add_f32 v[124:125], v[116:117], v[156:157]
	v_mul_f32_e32 v116, v123, v123
	v_fmac_f32_e32 v114, v118, v118
	v_fmac_f32_e32 v115, v120, v120
	v_mul_f32_e32 v117, v125, v125
	v_fmac_f32_e32 v116, v122, v122
	v_add_f32_e32 v114, v114, v115
	v_add_f32_e32 v114, v114, v116
	v_fmac_f32_e32 v117, v124, v124
	v_add_f32_e32 v114, v117, v114
	v_add_f32_e32 v114, v126, v114
	ds_bpermute_b32 v115, v146, v114
	global_store_dwordx4 v[170:171], v[118:121], off offset:512
	global_store_dwordx4 v[170:171], v[122:125], off offset:528
	v_cvt_pk_bf16_f32 v116, v118, v119
	v_cvt_pk_bf16_f32 v117, v120, v121
	s_waitcnt lgkmcnt(0)
	v_add_f32_e32 v114, v114, v115
	ds_bpermute_b32 v115, v147, v114
	v_cvt_pk_bf16_f32 v118, v122, v123
	v_cvt_pk_bf16_f32 v119, v124, v125
	global_store_dwordx4 v[168:169], v[116:119], off offset:256
	s_and_saveexec_b64 s[18:19], s[0:1]
	s_cbranch_execz .LBB0_1041
	v_lshl_add_u64 v[116:117], v[142:143], 2, s[22:23]
	s_waitcnt lgkmcnt(0)
	v_add_f32_e32 v114, v114, v115
	flat_atomic_add_f32 v[116:117], v114
.LBB0_1041:
	s_or_b64 exec, exec, s[18:19]
	v_or_b32_e32 v114, 16, v142
	s_waitcnt lgkmcnt(0)
	v_ashrrev_i32_e32 v115, 31, v114
	v_lshlrev_b64 v[116:117], 11, v[114:115]
	v_lshl_add_u64 v[124:125], v[116:117], 0, v[140:141]
	v_lshlrev_b64 v[126:127], 2, v[124:125]
	v_lshl_add_u64 v[128:129], s[42:43], 0, v[126:127]
	v_lshl_add_u64 v[124:125], v[124:125], 1, s[14:15]
	v_lshl_add_u64 v[126:127], s[54:55], 0, v[126:127]
	s_waitcnt vmcnt(16)
	v_mov_b32_e32 v116, v216
	v_mov_b32_e32 v117, v217
	v_mov_b32_e32 v118, v218
	v_mov_b32_e32 v119, v219
	v_mov_b32_e32 v120, v220
	v_mov_b32_e32 v121, v221
	v_mov_b32_e32 v122, v222
	v_mov_b32_e32 v123, v223
	s_mov_b32 s98, 0xa0000
	s_mov_b32 s99, 0
	v_lshl_add_u64 v[248:249], v[248:249], 0, s[98:99]
	global_load_dwordx4 v[216:219], v[248:249], off
	global_load_dwordx4 v[220:223], v[248:249], off offset:16
	v_pk_add_f32 v[112:113], v[112:113], v[118:119]
	v_pk_add_f32 v[110:111], v[110:111], v[116:117]
	v_pk_add_f32 v[108:109], v[108:109], v[122:123]
	v_pk_add_f32 v[106:107], v[106:107], v[120:121]
	global_store_dwordx4 v[126:127], v[110:113], off
	global_store_dwordx4 v[126:127], v[106:109], off offset:16
	v_cvt_pk_bf16_f32 v116, v110, v111
	v_cvt_pk_bf16_f32 v117, v112, v113
	v_cvt_pk_bf16_f32 v118, v106, v107
	v_cvt_pk_bf16_f32 v119, v108, v109
	global_store_dwordx4 v[124:125], v[116:119], off
	s_nop 0
	v_mul_f32_e32 v111, v111, v111
	v_mul_f32_e32 v113, v113, v113
	v_mul_f32_e32 v107, v107, v107
	v_fmac_f32_e32 v111, v110, v110
	v_fmac_f32_e32 v113, v112, v112
	v_mul_f32_e32 v109, v109, v109
	v_fmac_f32_e32 v107, v106, v106
	v_add_f32_e32 v106, v111, v113
	v_fmac_f32_e32 v109, v108, v108
	v_add_f32_e32 v106, v106, v107
	v_add_f32_e32 v110, v109, v106
	s_waitcnt vmcnt(19)
	v_mov_b32_e32 v116, v224
	v_mov_b32_e32 v117, v225
	v_mov_b32_e32 v118, v226
	v_mov_b32_e32 v119, v227
	v_mov_b32_e32 v120, v228
	v_mov_b32_e32 v121, v229
	v_mov_b32_e32 v122, v230
	v_mov_b32_e32 v123, v231
	global_load_dwordx4 v[224:227], v[248:249], off offset:512
	global_load_dwordx4 v[228:231], v[248:249], off offset:528
	v_pk_add_f32 v[104:105], v[104:105], v[118:119]
	v_pk_add_f32 v[102:103], v[102:103], v[116:117]
	v_pk_add_f32 v[106:107], v[98:99], v[120:121]
	v_mul_f32_e32 v98, v103, v103
	v_mul_f32_e32 v99, v105, v105
	v_pk_add_f32 v[108:109], v[100:101], v[122:123]
	v_mul_f32_e32 v100, v107, v107
	v_fmac_f32_e32 v98, v102, v102
	v_fmac_f32_e32 v99, v104, v104
	v_mul_f32_e32 v101, v109, v109
	v_fmac_f32_e32 v100, v106, v106
	v_add_f32_e32 v98, v98, v99
	v_add_f32_e32 v98, v98, v100
	v_fmac_f32_e32 v101, v108, v108
	v_add_f32_e32 v98, v101, v98
	v_add_f32_e32 v98, v110, v98
	ds_bpermute_b32 v99, v146, v98
	global_store_dwordx4 v[126:127], v[102:105], off offset:512
	global_store_dwordx4 v[126:127], v[106:109], off offset:528
	v_cvt_pk_bf16_f32 v100, v102, v103
	v_cvt_pk_bf16_f32 v101, v104, v105
	s_waitcnt lgkmcnt(0)
	v_add_f32_e32 v98, v98, v99
	ds_bpermute_b32 v99, v147, v98
	v_cvt_pk_bf16_f32 v102, v106, v107
	v_cvt_pk_bf16_f32 v103, v108, v109
	global_store_dwordx4 v[124:125], v[100:103], off offset:256
	s_and_saveexec_b64 s[18:19], s[0:1]
	s_cbranch_execz .LBB0_1043
	v_lshl_add_u64 v[100:101], v[114:115], 2, s[22:23]
	s_waitcnt lgkmcnt(0)
	v_add_f32_e32 v98, v98, v99
	flat_atomic_add_f32 v[100:101], v98
.LBB0_1043:
	s_or_b64 exec, exec, s[18:19]
	v_or_b32_e32 v98, 32, v142
	s_waitcnt lgkmcnt(0)
	v_ashrrev_i32_e32 v99, 31, v98
	v_lshlrev_b64 v[100:101], 11, v[98:99]
	v_lshl_add_u64 v[108:109], v[100:101], 0, v[140:141]
	v_lshlrev_b64 v[110:111], 2, v[108:109]
	v_lshl_add_u64 v[112:113], s[42:43], 0, v[110:111]
	v_lshl_add_u64 v[108:109], v[108:109], 1, s[14:15]
	v_lshl_add_u64 v[110:111], s[54:55], 0, v[110:111]
	s_waitcnt vmcnt(22)
	v_mov_b32_e32 v100, v232
	v_mov_b32_e32 v101, v233
	v_mov_b32_e32 v102, v234
	v_mov_b32_e32 v103, v235
	v_mov_b32_e32 v104, v236
	v_mov_b32_e32 v105, v237
	v_mov_b32_e32 v106, v238
	v_mov_b32_e32 v107, v239
	s_mov_b32 s98, 0x20000
	s_mov_b32 s99, 0
	v_lshl_add_u64 v[248:249], v[248:249], 0, s[98:99]
	global_load_dwordx4 v[232:235], v[248:249], off
	global_load_dwordx4 v[236:239], v[248:249], off offset:16
	v_pk_add_f32 v[94:95], v[94:95], v[102:103]
	v_pk_add_f32 v[92:93], v[92:93], v[100:101]
	v_pk_add_f32 v[90:91], v[90:91], v[106:107]
	v_pk_add_f32 v[88:89], v[88:89], v[104:105]
	global_store_dwordx4 v[110:111], v[92:95], off
	global_store_dwordx4 v[110:111], v[88:91], off offset:16
	v_cvt_pk_bf16_f32 v100, v92, v93
	v_cvt_pk_bf16_f32 v101, v94, v95
	v_cvt_pk_bf16_f32 v102, v88, v89
	v_cvt_pk_bf16_f32 v103, v90, v91
	global_store_dwordx4 v[108:109], v[100:103], off
	s_nop 0
	v_mul_f32_e32 v93, v93, v93
	v_mul_f32_e32 v95, v95, v95
	v_mul_f32_e32 v89, v89, v89
	v_fmac_f32_e32 v93, v92, v92
	v_fmac_f32_e32 v95, v94, v94
	v_mul_f32_e32 v91, v91, v91
	v_fmac_f32_e32 v89, v88, v88
	v_add_f32_e32 v88, v93, v95
	v_fmac_f32_e32 v91, v90, v90
	v_add_f32_e32 v88, v88, v89
	v_add_f32_e32 v92, v91, v88
	s_waitcnt vmcnt(25)
	v_mov_b32_e32 v100, v240
	v_mov_b32_e32 v101, v241
	v_mov_b32_e32 v102, v242
	v_mov_b32_e32 v103, v243
	v_mov_b32_e32 v104, v244
	v_mov_b32_e32 v105, v245
	v_mov_b32_e32 v106, v246
	v_mov_b32_e32 v107, v247
	global_load_dwordx4 v[240:243], v[248:249], off offset:512
	global_load_dwordx4 v[244:247], v[248:249], off offset:528
	v_pk_add_f32 v[86:87], v[86:87], v[102:103]
	v_pk_add_f32 v[84:85], v[84:85], v[100:101]
	v_pk_add_f32 v[88:89], v[80:81], v[104:105]
	v_mul_f32_e32 v80, v85, v85
	v_mul_f32_e32 v81, v87, v87
	v_pk_add_f32 v[90:91], v[82:83], v[106:107]
	v_mul_f32_e32 v82, v89, v89
	v_fmac_f32_e32 v80, v84, v84
	v_fmac_f32_e32 v81, v86, v86
	v_mul_f32_e32 v83, v91, v91
	v_fmac_f32_e32 v82, v88, v88
	v_add_f32_e32 v80, v80, v81
	v_add_f32_e32 v80, v80, v82
	v_fmac_f32_e32 v83, v90, v90
	v_add_f32_e32 v80, v83, v80
	v_add_f32_e32 v80, v92, v80
	ds_bpermute_b32 v81, v146, v80
	global_store_dwordx4 v[110:111], v[84:87], off offset:512
	global_store_dwordx4 v[110:111], v[88:91], off offset:528
	v_cvt_pk_bf16_f32 v82, v84, v85
	v_cvt_pk_bf16_f32 v83, v86, v87
	s_waitcnt lgkmcnt(0)
	v_add_f32_e32 v80, v80, v81
	ds_bpermute_b32 v81, v147, v80
	v_cvt_pk_bf16_f32 v84, v88, v89
	v_cvt_pk_bf16_f32 v85, v90, v91
	global_store_dwordx4 v[108:109], v[82:85], off offset:256
	s_and_saveexec_b64 s[18:19], s[0:1]
	s_mov_b64 s[84:85], s[88:89]
	s_mov_b32 s83, s94
	s_cbranch_execz .LBB0_1045
	v_lshl_add_u64 v[82:83], v[98:99], 2, s[22:23]
	s_waitcnt lgkmcnt(0)
	v_add_f32_e32 v80, v80, v81
	flat_atomic_add_f32 v[82:83], v80
.LBB0_1045:
	s_or_b64 exec, exec, s[18:19]
	v_or_b32_e32 v80, 48, v142
	s_waitcnt lgkmcnt(0)
	v_ashrrev_i32_e32 v81, 31, v80
	v_lshlrev_b64 v[82:83], 11, v[80:81]
	v_lshl_add_u64 v[90:91], v[82:83], 0, v[140:141]
	v_lshlrev_b64 v[92:93], 2, v[90:91]
	v_lshl_add_u64 v[94:95], s[42:43], 0, v[92:93]
	v_lshl_add_u64 v[90:91], v[90:91], 1, s[14:15]
	v_lshl_add_u64 v[92:93], s[54:55], 0, v[92:93]
	s_waitcnt vmcnt(28)
	v_mov_b32_e32 v82, v200
	v_mov_b32_e32 v83, v201
	v_mov_b32_e32 v84, v202
	v_mov_b32_e32 v85, v203
	v_mov_b32_e32 v86, v204
	v_mov_b32_e32 v87, v205
	v_mov_b32_e32 v88, v206
	v_mov_b32_e32 v89, v207
	s_mov_b32 s98, 0x20000
	s_mov_b32 s99, 0
	v_lshl_add_u64 v[248:249], v[248:249], 0, s[98:99]
	global_load_dwordx4 v[200:203], v[248:249], off
	global_load_dwordx4 v[204:207], v[248:249], off offset:16
	v_pk_add_f32 v[78:79], v[78:79], v[84:85]
	v_pk_add_f32 v[76:77], v[76:77], v[82:83]
	v_pk_add_f32 v[74:75], v[74:75], v[88:89]
	v_pk_add_f32 v[72:73], v[72:73], v[86:87]
	global_store_dwordx4 v[92:93], v[76:79], off
	global_store_dwordx4 v[92:93], v[72:75], off offset:16
	v_cvt_pk_bf16_f32 v82, v76, v77
	v_cvt_pk_bf16_f32 v83, v78, v79
	v_cvt_pk_bf16_f32 v84, v72, v73
	v_cvt_pk_bf16_f32 v85, v74, v75
	global_store_dwordx4 v[90:91], v[82:85], off
	s_nop 0
	v_mul_f32_e32 v77, v77, v77
	v_mul_f32_e32 v79, v79, v79
	v_mul_f32_e32 v73, v73, v73
	v_fmac_f32_e32 v77, v76, v76
	v_fmac_f32_e32 v79, v78, v78
	v_mul_f32_e32 v75, v75, v75
	v_fmac_f32_e32 v73, v72, v72
	v_add_f32_e32 v72, v77, v79
	v_fmac_f32_e32 v75, v74, v74
	v_add_f32_e32 v72, v72, v73
	v_add_f32_e32 v76, v75, v72
	s_waitcnt vmcnt(28)
	v_mov_b32_e32 v82, v208
	v_mov_b32_e32 v83, v209
	v_mov_b32_e32 v84, v210
	v_mov_b32_e32 v85, v211
	v_mov_b32_e32 v86, v212
	v_mov_b32_e32 v87, v213
	v_mov_b32_e32 v88, v214
	v_mov_b32_e32 v89, v215
	global_load_dwordx4 v[208:211], v[248:249], off offset:512
	global_load_dwordx4 v[212:215], v[248:249], off offset:528
	v_pk_add_f32 v[70:71], v[70:71], v[84:85]
	v_pk_add_f32 v[68:69], v[68:69], v[82:83]
	v_pk_add_f32 v[72:73], v[64:65], v[86:87]
	v_mul_f32_e32 v64, v69, v69
	v_mul_f32_e32 v65, v71, v71
	v_pk_add_f32 v[74:75], v[66:67], v[88:89]
	v_mul_f32_e32 v66, v73, v73
	v_fmac_f32_e32 v64, v68, v68
	v_fmac_f32_e32 v65, v70, v70
	v_mul_f32_e32 v67, v75, v75
	v_fmac_f32_e32 v66, v72, v72
	v_add_f32_e32 v64, v64, v65
	v_add_f32_e32 v64, v64, v66
	v_fmac_f32_e32 v67, v74, v74
	v_add_f32_e32 v64, v67, v64
	v_add_f32_e32 v64, v76, v64
	ds_bpermute_b32 v65, v146, v64
	global_store_dwordx4 v[92:93], v[68:71], off offset:512
	global_store_dwordx4 v[92:93], v[72:75], off offset:528
	v_cvt_pk_bf16_f32 v66, v68, v69
	v_cvt_pk_bf16_f32 v67, v70, v71
	s_waitcnt lgkmcnt(0)
	v_add_f32_e32 v64, v64, v65
	ds_bpermute_b32 v65, v147, v64
	v_cvt_pk_bf16_f32 v68, v72, v73
	v_cvt_pk_bf16_f32 v69, v74, v75
	global_store_dwordx4 v[90:91], v[66:69], off offset:256
	s_and_saveexec_b64 s[18:19], s[0:1]
	s_cbranch_execz .LBB0_1047
	v_lshl_add_u64 v[66:67], v[80:81], 2, s[22:23]
	s_waitcnt lgkmcnt(0)
	v_add_f32_e32 v64, v64, v65
	flat_atomic_add_f32 v[66:67], v64
.LBB0_1047:
	s_or_b64 exec, exec, s[18:19]
	v_add_u32_e32 v64, 0x80, v142
	s_waitcnt lgkmcnt(0)
	v_ashrrev_i32_e32 v65, 31, v64
	v_lshlrev_b64 v[66:67], 11, v[64:65]
	v_lshl_add_u64 v[74:75], v[66:67], 0, v[140:141]
	v_lshlrev_b64 v[76:77], 2, v[74:75]
	v_lshl_add_u64 v[78:79], s[42:43], 0, v[76:77]
	v_lshl_add_u64 v[74:75], v[74:75], 1, s[14:15]
	v_lshl_add_u64 v[76:77], s[54:55], 0, v[76:77]
	s_waitcnt vmcnt(28)
	v_mov_b32_e32 v66, v216
	v_mov_b32_e32 v67, v217
	v_mov_b32_e32 v68, v218
	v_mov_b32_e32 v69, v219
	v_mov_b32_e32 v70, v220
	v_mov_b32_e32 v71, v221
	v_mov_b32_e32 v72, v222
	v_mov_b32_e32 v73, v223
	s_mov_b32 s98, 0x20000
	s_mov_b32 s99, 0
	v_lshl_add_u64 v[248:249], v[248:249], 0, s[98:99]
	global_load_dwordx4 v[216:219], v[248:249], off
	global_load_dwordx4 v[220:223], v[248:249], off offset:16
	v_pk_add_f32 v[62:63], v[62:63], v[68:69]
	v_pk_add_f32 v[60:61], v[60:61], v[66:67]
	v_pk_add_f32 v[58:59], v[58:59], v[72:73]
	v_pk_add_f32 v[56:57], v[56:57], v[70:71]
	global_store_dwordx4 v[76:77], v[60:63], off
	global_store_dwordx4 v[76:77], v[56:59], off offset:16
	v_cvt_pk_bf16_f32 v66, v60, v61
	v_cvt_pk_bf16_f32 v67, v62, v63
	v_cvt_pk_bf16_f32 v68, v56, v57
	v_cvt_pk_bf16_f32 v69, v58, v59
	global_store_dwordx4 v[74:75], v[66:69], off
	s_nop 0
	v_mul_f32_e32 v61, v61, v61
	v_mul_f32_e32 v63, v63, v63
	v_mul_f32_e32 v57, v57, v57
	v_fmac_f32_e32 v61, v60, v60
	v_fmac_f32_e32 v63, v62, v62
	v_mul_f32_e32 v59, v59, v59
	v_fmac_f32_e32 v57, v56, v56
	v_add_f32_e32 v56, v61, v63
	v_fmac_f32_e32 v59, v58, v58
	v_add_f32_e32 v56, v56, v57
	v_add_f32_e32 v60, v59, v56
	s_waitcnt vmcnt(28)
	v_mov_b32_e32 v66, v224
	v_mov_b32_e32 v67, v225
	v_mov_b32_e32 v68, v226
	v_mov_b32_e32 v69, v227
	v_mov_b32_e32 v70, v228
	v_mov_b32_e32 v71, v229
	v_mov_b32_e32 v72, v230
	v_mov_b32_e32 v73, v231
	global_load_dwordx4 v[224:227], v[248:249], off offset:512
	global_load_dwordx4 v[228:231], v[248:249], off offset:528
	v_pk_add_f32 v[54:55], v[54:55], v[68:69]
	v_pk_add_f32 v[52:53], v[52:53], v[66:67]
	v_pk_add_f32 v[56:57], v[48:49], v[70:71]
	v_mul_f32_e32 v48, v53, v53
	v_mul_f32_e32 v49, v55, v55
	v_pk_add_f32 v[58:59], v[50:51], v[72:73]
	v_mul_f32_e32 v50, v57, v57
	v_fmac_f32_e32 v48, v52, v52
	v_fmac_f32_e32 v49, v54, v54
	v_mul_f32_e32 v51, v59, v59
	v_fmac_f32_e32 v50, v56, v56
	v_add_f32_e32 v48, v48, v49
	v_add_f32_e32 v48, v48, v50
	v_fmac_f32_e32 v51, v58, v58
	v_add_f32_e32 v48, v51, v48
	v_add_f32_e32 v48, v60, v48
	ds_bpermute_b32 v49, v146, v48
	global_store_dwordx4 v[76:77], v[52:55], off offset:512
	global_store_dwordx4 v[76:77], v[56:59], off offset:528
	v_cvt_pk_bf16_f32 v50, v52, v53
	v_cvt_pk_bf16_f32 v51, v54, v55
	s_waitcnt lgkmcnt(0)
	v_add_f32_e32 v48, v48, v49
	ds_bpermute_b32 v49, v147, v48
	v_cvt_pk_bf16_f32 v52, v56, v57
	v_cvt_pk_bf16_f32 v53, v58, v59
	global_store_dwordx4 v[74:75], v[50:53], off offset:256
	s_and_saveexec_b64 s[18:19], s[0:1]
	s_cbranch_execz .LBB0_1049
	v_lshl_add_u64 v[50:51], v[64:65], 2, s[22:23]
	s_waitcnt lgkmcnt(0)
	v_add_f32_e32 v48, v48, v49
	flat_atomic_add_f32 v[50:51], v48
.LBB0_1049:
	s_or_b64 exec, exec, s[18:19]
	v_add_u32_e32 v48, 0x90, v142
	s_waitcnt lgkmcnt(0)
	v_ashrrev_i32_e32 v49, 31, v48
	v_lshlrev_b64 v[50:51], 11, v[48:49]
	v_lshl_add_u64 v[58:59], v[50:51], 0, v[140:141]
	v_lshlrev_b64 v[60:61], 2, v[58:59]
	v_lshl_add_u64 v[62:63], s[42:43], 0, v[60:61]
	v_lshl_add_u64 v[58:59], v[58:59], 1, s[14:15]
	v_lshl_add_u64 v[60:61], s[54:55], 0, v[60:61]
	s_waitcnt vmcnt(28)
	v_mov_b32_e32 v50, v232
	v_mov_b32_e32 v51, v233
	v_mov_b32_e32 v52, v234
	v_mov_b32_e32 v53, v235
	v_mov_b32_e32 v54, v236
	v_mov_b32_e32 v55, v237
	v_mov_b32_e32 v56, v238
	v_mov_b32_e32 v57, v239
	v_pk_add_f32 v[46:47], v[46:47], v[52:53]
	v_pk_add_f32 v[44:45], v[44:45], v[50:51]
	v_pk_add_f32 v[42:43], v[42:43], v[56:57]
	v_pk_add_f32 v[40:41], v[40:41], v[54:55]
	global_store_dwordx4 v[60:61], v[44:47], off
	global_store_dwordx4 v[60:61], v[40:43], off offset:16
	v_cvt_pk_bf16_f32 v50, v44, v45
	v_cvt_pk_bf16_f32 v51, v46, v47
	v_cvt_pk_bf16_f32 v52, v40, v41
	v_cvt_pk_bf16_f32 v53, v42, v43
	global_store_dwordx4 v[58:59], v[50:53], off
	s_nop 0
	v_mul_f32_e32 v45, v45, v45
	v_mul_f32_e32 v47, v47, v47
	v_mul_f32_e32 v41, v41, v41
	v_fmac_f32_e32 v45, v44, v44
	v_fmac_f32_e32 v47, v46, v46
	v_mul_f32_e32 v43, v43, v43
	v_fmac_f32_e32 v41, v40, v40
	v_add_f32_e32 v40, v45, v47
	v_fmac_f32_e32 v43, v42, v42
	v_add_f32_e32 v40, v40, v41
	v_add_f32_e32 v44, v43, v40
	s_waitcnt vmcnt(26)
	v_mov_b32_e32 v50, v240
	v_mov_b32_e32 v51, v241
	v_mov_b32_e32 v52, v242
	v_mov_b32_e32 v53, v243
	v_mov_b32_e32 v54, v244
	v_mov_b32_e32 v55, v245
	v_mov_b32_e32 v56, v246
	v_mov_b32_e32 v57, v247
	v_pk_add_f32 v[38:39], v[38:39], v[52:53]
	v_pk_add_f32 v[36:37], v[36:37], v[50:51]
	v_pk_add_f32 v[40:41], v[32:33], v[54:55]
	v_mul_f32_e32 v32, v37, v37
	v_mul_f32_e32 v33, v39, v39
	v_pk_add_f32 v[42:43], v[34:35], v[56:57]
	v_mul_f32_e32 v34, v41, v41
	v_fmac_f32_e32 v32, v36, v36
	v_fmac_f32_e32 v33, v38, v38
	v_mul_f32_e32 v35, v43, v43
	v_fmac_f32_e32 v34, v40, v40
	v_add_f32_e32 v32, v32, v33
	v_add_f32_e32 v32, v32, v34
	v_fmac_f32_e32 v35, v42, v42
	v_add_f32_e32 v32, v35, v32
	v_add_f32_e32 v32, v44, v32
	ds_bpermute_b32 v33, v146, v32
	global_store_dwordx4 v[60:61], v[36:39], off offset:512
	global_store_dwordx4 v[60:61], v[40:43], off offset:528
	v_cvt_pk_bf16_f32 v34, v36, v37
	v_cvt_pk_bf16_f32 v35, v38, v39
	s_waitcnt lgkmcnt(0)
	v_add_f32_e32 v32, v32, v33
	ds_bpermute_b32 v33, v147, v32
	v_cvt_pk_bf16_f32 v36, v40, v41
	v_cvt_pk_bf16_f32 v37, v42, v43
	global_store_dwordx4 v[58:59], v[34:37], off offset:256
	s_and_saveexec_b64 s[18:19], s[0:1]
	s_cbranch_execz .LBB0_1051
	v_lshl_add_u64 v[34:35], v[48:49], 2, s[22:23]
	s_waitcnt lgkmcnt(0)
	v_add_f32_e32 v32, v32, v33
	flat_atomic_add_f32 v[34:35], v32
.LBB0_1051:
	s_or_b64 exec, exec, s[18:19]
	v_add_u32_e32 v32, 0xa0, v142
	s_waitcnt lgkmcnt(0)
	v_ashrrev_i32_e32 v33, 31, v32
	v_lshlrev_b64 v[34:35], 11, v[32:33]
	v_lshl_add_u64 v[42:43], v[34:35], 0, v[140:141]
	v_lshlrev_b64 v[44:45], 2, v[42:43]
	v_lshl_add_u64 v[46:47], s[42:43], 0, v[44:45]
	v_lshl_add_u64 v[42:43], v[42:43], 1, s[14:15]
	v_lshl_add_u64 v[44:45], s[54:55], 0, v[44:45]
	s_waitcnt vmcnt(24)
	v_mov_b32_e32 v34, v200
	v_mov_b32_e32 v35, v201
	v_mov_b32_e32 v36, v202
	v_mov_b32_e32 v37, v203
	v_mov_b32_e32 v38, v204
	v_mov_b32_e32 v39, v205
	v_mov_b32_e32 v40, v206
	v_mov_b32_e32 v41, v207
	v_pk_add_f32 v[30:31], v[30:31], v[36:37]
	v_pk_add_f32 v[28:29], v[28:29], v[34:35]
	v_pk_add_f32 v[26:27], v[26:27], v[40:41]
	v_pk_add_f32 v[24:25], v[24:25], v[38:39]
	global_store_dwordx4 v[44:45], v[28:31], off
	global_store_dwordx4 v[44:45], v[24:27], off offset:16
	v_cvt_pk_bf16_f32 v34, v28, v29
	v_cvt_pk_bf16_f32 v35, v30, v31
	v_cvt_pk_bf16_f32 v36, v24, v25
	v_cvt_pk_bf16_f32 v37, v26, v27
	global_store_dwordx4 v[42:43], v[34:37], off
	s_nop 0
	v_mul_f32_e32 v29, v29, v29
	v_mul_f32_e32 v31, v31, v31
	v_mul_f32_e32 v25, v25, v25
	v_fmac_f32_e32 v29, v28, v28
	v_fmac_f32_e32 v31, v30, v30
	v_mul_f32_e32 v27, v27, v27
	v_fmac_f32_e32 v25, v24, v24
	v_add_f32_e32 v24, v29, v31
	v_fmac_f32_e32 v27, v26, v26
	v_add_f32_e32 v24, v24, v25
	v_add_f32_e32 v28, v27, v24
	s_waitcnt vmcnt(22)
	v_mov_b32_e32 v34, v208
	v_mov_b32_e32 v35, v209
	v_mov_b32_e32 v36, v210
	v_mov_b32_e32 v37, v211
	v_mov_b32_e32 v38, v212
	v_mov_b32_e32 v39, v213
	v_mov_b32_e32 v40, v214
	v_mov_b32_e32 v41, v215
	v_pk_add_f32 v[22:23], v[22:23], v[36:37]
	v_pk_add_f32 v[20:21], v[20:21], v[34:35]
	v_pk_add_f32 v[24:25], v[16:17], v[38:39]
	v_mul_f32_e32 v16, v21, v21
	v_mul_f32_e32 v17, v23, v23
	v_pk_add_f32 v[26:27], v[18:19], v[40:41]
	v_mul_f32_e32 v18, v25, v25
	v_fmac_f32_e32 v16, v20, v20
	v_fmac_f32_e32 v17, v22, v22
	v_mul_f32_e32 v19, v27, v27
	v_fmac_f32_e32 v18, v24, v24
	v_add_f32_e32 v16, v16, v17
	v_add_f32_e32 v16, v16, v18
	v_fmac_f32_e32 v19, v26, v26
	v_add_f32_e32 v16, v19, v16
	v_add_f32_e32 v16, v28, v16
	ds_bpermute_b32 v17, v146, v16
	global_store_dwordx4 v[44:45], v[20:23], off offset:512
	global_store_dwordx4 v[44:45], v[24:27], off offset:528
	v_cvt_pk_bf16_f32 v18, v20, v21
	v_cvt_pk_bf16_f32 v19, v22, v23
	s_waitcnt lgkmcnt(0)
	v_add_f32_e32 v16, v16, v17
	ds_bpermute_b32 v17, v147, v16
	v_cvt_pk_bf16_f32 v20, v24, v25
	v_cvt_pk_bf16_f32 v21, v26, v27
	global_store_dwordx4 v[42:43], v[18:21], off offset:256
	s_and_saveexec_b64 s[18:19], s[0:1]
	s_cbranch_execz .LBB0_1053
	v_lshl_add_u64 v[18:19], v[32:33], 2, s[22:23]
	s_waitcnt lgkmcnt(0)
	v_add_f32_e32 v16, v16, v17
	flat_atomic_add_f32 v[18:19], v16
.LBB0_1053:
	s_or_b64 exec, exec, s[18:19]
	v_add_u32_e32 v16, 0xb0, v142
	s_waitcnt lgkmcnt(0)
	v_ashrrev_i32_e32 v17, 31, v16
	v_lshlrev_b64 v[18:19], 11, v[16:17]
	v_lshl_add_u64 v[26:27], v[18:19], 0, v[140:141]
	v_lshlrev_b64 v[28:29], 2, v[26:27]
	v_lshl_add_u64 v[30:31], s[42:43], 0, v[28:29]
	v_lshl_add_u64 v[26:27], v[26:27], 1, s[14:15]
	v_lshl_add_u64 v[28:29], s[54:55], 0, v[28:29]
	s_waitcnt vmcnt(20)
	v_mov_b32_e32 v18, v216
	v_mov_b32_e32 v19, v217
	v_mov_b32_e32 v20, v218
	v_mov_b32_e32 v21, v219
	v_mov_b32_e32 v22, v220
	v_mov_b32_e32 v23, v221
	v_mov_b32_e32 v24, v222
	v_mov_b32_e32 v25, v223
	v_pk_add_f32 v[14:15], v[14:15], v[20:21]
	v_pk_add_f32 v[12:13], v[12:13], v[18:19]
	v_pk_add_f32 v[10:11], v[10:11], v[24:25]
	v_pk_add_f32 v[8:9], v[8:9], v[22:23]
	global_store_dwordx4 v[28:29], v[12:15], off
	global_store_dwordx4 v[28:29], v[8:11], off offset:16
	v_cvt_pk_bf16_f32 v18, v12, v13
	v_cvt_pk_bf16_f32 v19, v14, v15
	v_cvt_pk_bf16_f32 v20, v8, v9
	v_cvt_pk_bf16_f32 v21, v10, v11
	global_store_dwordx4 v[26:27], v[18:21], off
	s_nop 0
	v_mul_f32_e32 v13, v13, v13
	v_mul_f32_e32 v15, v15, v15
	v_mul_f32_e32 v9, v9, v9
	v_fmac_f32_e32 v13, v12, v12
	v_fmac_f32_e32 v15, v14, v14
	v_mul_f32_e32 v11, v11, v11
	v_fmac_f32_e32 v9, v8, v8
	v_add_f32_e32 v8, v13, v15
	v_fmac_f32_e32 v11, v10, v10
	v_add_f32_e32 v8, v8, v9
	v_add_f32_e32 v12, v11, v8
	s_waitcnt vmcnt(18)
	v_mov_b32_e32 v18, v224
	v_mov_b32_e32 v19, v225
	v_mov_b32_e32 v20, v226
	v_mov_b32_e32 v21, v227
	v_mov_b32_e32 v22, v228
	v_mov_b32_e32 v23, v229
	v_mov_b32_e32 v24, v230
	v_mov_b32_e32 v25, v231
	v_pk_add_f32 v[6:7], v[6:7], v[20:21]
	v_pk_add_f32 v[4:5], v[4:5], v[18:19]
	v_pk_add_f32 v[8:9], v[0:1], v[22:23]
	v_mul_f32_e32 v0, v5, v5
	v_mul_f32_e32 v1, v7, v7
	v_pk_add_f32 v[10:11], v[2:3], v[24:25]
	v_mul_f32_e32 v2, v9, v9
	v_fmac_f32_e32 v0, v4, v4
	v_fmac_f32_e32 v1, v6, v6
	v_mul_f32_e32 v3, v11, v11
	v_fmac_f32_e32 v2, v8, v8
	v_add_f32_e32 v0, v0, v1
	v_add_f32_e32 v0, v0, v2
	v_fmac_f32_e32 v3, v10, v10
	v_add_f32_e32 v0, v3, v0
	v_add_f32_e32 v0, v12, v0
	ds_bpermute_b32 v1, v146, v0
	global_store_dwordx4 v[28:29], v[4:7], off offset:512
	global_store_dwordx4 v[28:29], v[8:11], off offset:528
	v_cvt_pk_bf16_f32 v2, v4, v5
	v_cvt_pk_bf16_f32 v3, v6, v7
	s_waitcnt lgkmcnt(0)
	v_add_f32_e32 v0, v0, v1
	ds_bpermute_b32 v1, v147, v0
	v_cvt_pk_bf16_f32 v4, v8, v9
	v_cvt_pk_bf16_f32 v5, v10, v11
	global_store_dwordx4 v[26:27], v[2:5], off offset:256
	s_and_saveexec_b64 s[18:19], s[0:1]
	s_cbranch_execz .LBB0_1055
	v_lshl_add_u64 v[2:3], v[16:17], 2, s[22:23]
	s_waitcnt lgkmcnt(0)
	v_add_f32_e32 v0, v0, v1
	flat_atomic_add_f32 v[2:3], v0

.LBB0_1360:
	v_mbcnt_lo_u32_b32 v0, -1, 0
	v_mbcnt_hi_u32_b32 v0, -1, v0
	s_waitcnt vmcnt(0)
	v_readlane_b32 s0, v253, 11
	s_barrier
	s_nop 0
	v_cmp_eq_u32_e32 vcc, s0, v0
	s_bitcmp1_b32 s83, 0
	s_cselect_b64 vcc, vcc, 0
	s_and_saveexec_b64 s[0:1], vcc
	s_cbranch_execnz .LBB0_1361
	s_getpc_b64 s[98:99]
